# phase 10 gate/merge epilogue: all 16 branch-output loads issued up front into dead fragment registers (one wait instead of 8 dependent load-wait rounds per tile); on top of v54
# baseline (speedup 1.0000x reference)
.LBB0_898:
	ds_read_b128 v[136:139], v151
	ds_read_b128 v[168:171], v151 offset:1024
	ds_read_b128 v[172:175], v151 offset:2048
	ds_read_b128 v[176:179], v151 offset:3072
	s_add_u32 s28, s46, 0xfffc0080
	s_addc_u32 s29, s47, -1
	s_cmp_eq_u32 s74, 12
	s_cselect_b32 s51, s19, s29
	s_cselect_b32 s50, s21, s28
	s_cselect_b32 s49, s23, s73
	s_cselect_b32 s48, s27, s72
	v_lshl_add_u64 v[140:141], s[46:47], 0, v[128:129]
	s_add_i32 m0, s45, 0xc000
	ds_read_b128 v[194:197], v153
	ds_read_b128 v[198:201], v153 offset:1024
	ds_read_b128 v[202:205], v153 offset:2048
	ds_read_b128 v[206:209], v153 offset:3072
	ds_read_b128 v[210:213], v153 offset:4096
	ds_read_b128 v[214:217], v153 offset:5120
	ds_read_b128 v[218:221], v153 offset:6144
	ds_read_b128 v[222:225], v153 offset:7168
	global_load_lds_dwordx4 v[140:141], off
	v_lshl_add_u64 v[140:141], s[46:47], 0, v[130:131]
	s_add_i32 m0, s45, 0xe000
	s_nop 0
	global_load_lds_dwordx4 v[140:141], off
	s_waitcnt lgkmcnt(8)
	s_barrier
	s_waitcnt lgkmcnt(0)
	s_setprio 1
	s_waitcnt lgkmcnt(0)
	v_mfma_f32_16x16x32_bf16 v[124:127], v[136:139], v[194:197], v[124:127]
	v_mfma_f32_16x16x32_bf16 v[120:123], v[172:175], v[194:197], v[120:123]
	v_mfma_f32_16x16x32_bf16 v[108:111], v[136:139], v[202:205], v[108:111]
	v_mfma_f32_16x16x32_bf16 v[104:107], v[172:175], v[202:205], v[104:107]
	v_mfma_f32_16x16x32_bf16 v[92:95], v[136:139], v[210:213], v[92:95]
	v_mfma_f32_16x16x32_bf16 v[88:91], v[172:175], v[210:213], v[88:91]
	v_mfma_f32_16x16x32_bf16 v[76:79], v[136:139], v[218:221], v[76:79]
	v_mfma_f32_16x16x32_bf16 v[72:75], v[172:175], v[218:221], v[72:75]
	v_mfma_f32_16x16x32_bf16 v[124:127], v[168:171], v[198:201], v[124:127]
	v_mfma_f32_16x16x32_bf16 v[120:123], v[176:179], v[198:201], v[120:123]
	v_mfma_f32_16x16x32_bf16 v[108:111], v[168:171], v[206:209], v[108:111]
	v_mfma_f32_16x16x32_bf16 v[104:107], v[176:179], v[206:209], v[104:107]
	v_mfma_f32_16x16x32_bf16 v[92:95], v[168:171], v[214:217], v[92:95]
	v_mfma_f32_16x16x32_bf16 v[88:91], v[176:179], v[214:217], v[88:91]
	v_mfma_f32_16x16x32_bf16 v[76:79], v[168:171], v[222:225], v[76:79]
	v_mfma_f32_16x16x32_bf16 v[72:75], v[176:179], v[222:225], v[72:75]
	s_setprio 0
	s_barrier
	s_add_i32 s28, s70, s53
	v_lshl_add_u64 v[140:141], s[48:49], 0, v[158:159]
	s_mov_b32 m0, s28
	ds_read_b128 v[226:229], v155
	ds_read_b128 v[230:233], v155 offset:1024
	ds_read_b128 v[234:237], v155 offset:2048
	ds_read_b128 v[238:241], v155 offset:3072
	global_load_lds_dwordx4 v[140:141], off
	v_lshl_add_u64 v[242:243], s[48:49], 0, v[162:163]
	s_add_i32 m0, s28, 0x2000
	s_nop 0
	global_load_lds_dwordx4 v[242:243], off
	s_barrier
	s_waitcnt lgkmcnt(0)
	s_setprio 1
	s_waitcnt lgkmcnt(0)
	v_mfma_f32_16x16x32_bf16 v[116:119], v[226:229], v[194:197], v[116:119]
	v_mfma_f32_16x16x32_bf16 v[112:115], v[234:237], v[194:197], v[112:115]
	v_mfma_f32_16x16x32_bf16 v[100:103], v[226:229], v[202:205], v[100:103]
	v_mfma_f32_16x16x32_bf16 v[96:99], v[234:237], v[202:205], v[96:99]
	v_mfma_f32_16x16x32_bf16 v[84:87], v[226:229], v[210:213], v[84:87]
	v_mfma_f32_16x16x32_bf16 v[80:83], v[234:237], v[210:213], v[80:83]
	v_mfma_f32_16x16x32_bf16 v[68:71], v[226:229], v[218:221], v[68:71]
	v_mfma_f32_16x16x32_bf16 v[64:67], v[234:237], v[218:221], v[64:67]
	v_mfma_f32_16x16x32_bf16 v[116:119], v[230:233], v[198:201], v[116:119]
	v_mfma_f32_16x16x32_bf16 v[112:115], v[238:241], v[198:201], v[112:115]
	v_mfma_f32_16x16x32_bf16 v[100:103], v[230:233], v[206:209], v[100:103]
	v_mfma_f32_16x16x32_bf16 v[96:99], v[238:241], v[206:209], v[96:99]
	v_mfma_f32_16x16x32_bf16 v[84:87], v[230:233], v[214:217], v[84:87]
	v_mfma_f32_16x16x32_bf16 v[80:83], v[238:241], v[214:217], v[80:83]
	v_mfma_f32_16x16x32_bf16 v[68:71], v[230:233], v[222:225], v[68:71]
	v_mfma_f32_16x16x32_bf16 v[64:67], v[238:241], v[222:225], v[64:67]
	s_setprio 0
	s_mov_b32 m0, s45
	v_lshl_add_u64 v[244:245], s[50:51], 0, v[156:157]
	s_barrier
	ds_read_b128 v[194:197], v153 offset:16384
	ds_read_b128 v[198:201], v153 offset:17408
	ds_read_b128 v[202:205], v153 offset:18432
	ds_read_b128 v[206:209], v153 offset:19456
	ds_read_b128 v[210:213], v153 offset:20480
	ds_read_b128 v[214:217], v153 offset:21504
	ds_read_b128 v[218:221], v153 offset:22528
	ds_read_b128 v[222:225], v153 offset:23552
	global_load_lds_dwordx4 v[244:245], off
	v_lshl_add_u64 v[246:247], s[50:51], 0, v[160:161]
	s_mov_b32 m0, s4
	s_nop 0
	global_load_lds_dwordx4 v[246:247], off
	s_barrier
	s_waitcnt lgkmcnt(0)
	s_setprio 1
	s_waitcnt lgkmcnt(0)
	v_mfma_f32_16x16x32_bf16 v[60:63], v[136:139], v[194:197], v[60:63]
	v_mfma_f32_16x16x32_bf16 v[56:59], v[172:175], v[194:197], v[56:59]
	v_mfma_f32_16x16x32_bf16 v[44:47], v[136:139], v[202:205], v[44:47]
	v_mfma_f32_16x16x32_bf16 v[40:43], v[172:175], v[202:205], v[40:43]
	v_mfma_f32_16x16x32_bf16 v[28:31], v[136:139], v[210:213], v[28:31]
	v_mfma_f32_16x16x32_bf16 v[24:27], v[172:175], v[210:213], v[24:27]
	v_mfma_f32_16x16x32_bf16 v[12:15], v[136:139], v[218:221], v[12:15]
	v_mfma_f32_16x16x32_bf16 v[8:11], v[172:175], v[218:221], v[8:11]
	v_mfma_f32_16x16x32_bf16 v[60:63], v[168:171], v[198:201], v[60:63]
	v_mfma_f32_16x16x32_bf16 v[56:59], v[176:179], v[198:201], v[56:59]
	v_mfma_f32_16x16x32_bf16 v[44:47], v[168:171], v[206:209], v[44:47]
	v_mfma_f32_16x16x32_bf16 v[40:43], v[176:179], v[206:209], v[40:43]
	v_mfma_f32_16x16x32_bf16 v[28:31], v[168:171], v[214:217], v[28:31]
	v_mfma_f32_16x16x32_bf16 v[24:27], v[176:179], v[214:217], v[24:27]
	v_mfma_f32_16x16x32_bf16 v[12:15], v[168:171], v[222:225], v[12:15]
	v_mfma_f32_16x16x32_bf16 v[8:11], v[176:179], v[222:225], v[8:11]
	s_setprio 0
	s_barrier
	s_add_u32 s28, s48, 0x40000
	s_addc_u32 s29, s49, 0
	s_add_i32 s75, s71, s53
	v_lshl_add_u64 v[136:137], s[28:29], 0, v[158:159]
	s_mov_b32 m0, s75
	s_nop 0
	global_load_lds_dwordx4 v[136:137], off
	v_lshl_add_u64 v[136:137], s[28:29], 0, v[162:163]
	s_add_i32 m0, s75, 0x2000
	s_nop 0
	global_load_lds_dwordx4 v[136:137], off
	s_waitcnt vmcnt(6)
	s_barrier
	s_setprio 1
	v_mfma_f32_16x16x32_bf16 v[52:55], v[226:229], v[194:197], v[52:55]
	v_mfma_f32_16x16x32_bf16 v[48:51], v[234:237], v[194:197], v[48:51]
	v_mfma_f32_16x16x32_bf16 v[36:39], v[226:229], v[202:205], v[36:39]
	v_mfma_f32_16x16x32_bf16 v[32:35], v[234:237], v[202:205], v[32:35]
	v_mfma_f32_16x16x32_bf16 v[20:23], v[226:229], v[210:213], v[20:23]
	v_mfma_f32_16x16x32_bf16 v[16:19], v[234:237], v[210:213], v[16:19]
	v_mfma_f32_16x16x32_bf16 v[4:7], v[226:229], v[218:221], v[4:7]
	v_mfma_f32_16x16x32_bf16 v[0:3], v[234:237], v[218:221], v[0:3]
	v_mfma_f32_16x16x32_bf16 v[52:55], v[230:233], v[198:201], v[52:55]
	v_mfma_f32_16x16x32_bf16 v[48:51], v[238:241], v[198:201], v[48:51]
	v_mfma_f32_16x16x32_bf16 v[36:39], v[230:233], v[206:209], v[36:39]
	v_mfma_f32_16x16x32_bf16 v[32:35], v[238:241], v[206:209], v[32:35]
	v_mfma_f32_16x16x32_bf16 v[20:23], v[230:233], v[214:217], v[20:23]
	v_mfma_f32_16x16x32_bf16 v[16:19], v[238:241], v[214:217], v[16:19]
	v_mfma_f32_16x16x32_bf16 v[4:7], v[230:233], v[222:225], v[4:7]
	v_mfma_f32_16x16x32_bf16 v[0:3], v[238:241], v[222:225], v[0:3]
	s_setprio 0
	s_add_i32 s75, 0, 0x18000
	v_add_u32_e32 v164, s75, v143
	s_barrier
	ds_read_b128 v[136:139], v164
	ds_read_b128 v[168:171], v164 offset:1024
	ds_read_b128 v[172:175], v164 offset:2048
	ds_read_b128 v[176:179], v164 offset:3072
	s_add_u32 s28, s50, 0x40000
	s_addc_u32 s29, s51, 0
	s_mov_b32 m0, s5
	v_lshl_add_u64 v[226:227], s[28:29], 0, v[156:157]
	ds_read_b128 v[194:197], v153 offset:32768
	ds_read_b128 v[198:201], v153 offset:33792
	ds_read_b128 v[202:205], v153 offset:34816
	ds_read_b128 v[206:209], v153 offset:35840
	ds_read_b128 v[210:213], v153 offset:36864
	ds_read_b128 v[214:217], v153 offset:37888
	ds_read_b128 v[218:221], v153 offset:38912
	ds_read_b128 v[222:225], v153 offset:39936
	global_load_lds_dwordx4 v[226:227], off
	v_lshl_add_u64 v[226:227], s[28:29], 0, v[160:161]
	s_mov_b32 m0, s55
	s_nop 0
	global_load_lds_dwordx4 v[226:227], off
	s_waitcnt lgkmcnt(8)
	s_barrier
	s_waitcnt lgkmcnt(0)
	s_setprio 1
	s_waitcnt lgkmcnt(0)
	v_mfma_f32_16x16x32_bf16 v[124:127], v[136:139], v[194:197], v[124:127]
	v_mfma_f32_16x16x32_bf16 v[120:123], v[172:175], v[194:197], v[120:123]
	v_mfma_f32_16x16x32_bf16 v[108:111], v[136:139], v[202:205], v[108:111]
	v_mfma_f32_16x16x32_bf16 v[104:107], v[172:175], v[202:205], v[104:107]
	v_mfma_f32_16x16x32_bf16 v[92:95], v[136:139], v[210:213], v[92:95]
	v_mfma_f32_16x16x32_bf16 v[88:91], v[172:175], v[210:213], v[88:91]
	v_mfma_f32_16x16x32_bf16 v[76:79], v[136:139], v[218:221], v[76:79]
	v_mfma_f32_16x16x32_bf16 v[72:75], v[172:175], v[218:221], v[72:75]
	v_mfma_f32_16x16x32_bf16 v[124:127], v[168:171], v[198:201], v[124:127]
	v_mfma_f32_16x16x32_bf16 v[120:123], v[176:179], v[198:201], v[120:123]
	v_mfma_f32_16x16x32_bf16 v[108:111], v[168:171], v[206:209], v[108:111]
	v_mfma_f32_16x16x32_bf16 v[104:107], v[176:179], v[206:209], v[104:107]
	v_mfma_f32_16x16x32_bf16 v[92:95], v[168:171], v[214:217], v[92:95]
	v_mfma_f32_16x16x32_bf16 v[88:91], v[176:179], v[214:217], v[88:91]
	v_mfma_f32_16x16x32_bf16 v[76:79], v[168:171], v[222:225], v[76:79]
	v_mfma_f32_16x16x32_bf16 v[72:75], v[176:179], v[222:225], v[72:75]
	s_setprio 0
	s_barrier
	s_add_i32 s50, 0, 0x1c000
	s_add_i32 s28, s75, s53
	v_add_u32_e32 v164, s50, v143
	v_lshl_add_u64 v[140:141], v[140:141], 0, s[10:11]
	s_mov_b32 m0, s28
	ds_read_b128 v[226:229], v164
	ds_read_b128 v[230:233], v164 offset:1024
	ds_read_b128 v[234:237], v164 offset:2048
	ds_read_b128 v[238:241], v164 offset:3072
	global_load_lds_dwordx4 v[140:141], off
	v_lshl_add_u64 v[140:141], v[242:243], 0, s[10:11]
	s_add_i32 m0, s28, 0x2000
	s_nop 0
	global_load_lds_dwordx4 v[140:141], off
	s_barrier
	s_waitcnt lgkmcnt(0)
	s_setprio 1
	s_waitcnt lgkmcnt(0)
	v_mfma_f32_16x16x32_bf16 v[116:119], v[226:229], v[194:197], v[116:119]
	v_mfma_f32_16x16x32_bf16 v[112:115], v[234:237], v[194:197], v[112:115]
	v_mfma_f32_16x16x32_bf16 v[100:103], v[226:229], v[202:205], v[100:103]
	v_mfma_f32_16x16x32_bf16 v[96:99], v[234:237], v[202:205], v[96:99]
	v_mfma_f32_16x16x32_bf16 v[84:87], v[226:229], v[210:213], v[84:87]
	v_mfma_f32_16x16x32_bf16 v[80:83], v[234:237], v[210:213], v[80:83]
	v_mfma_f32_16x16x32_bf16 v[68:71], v[226:229], v[218:221], v[68:71]
	v_mfma_f32_16x16x32_bf16 v[64:67], v[234:237], v[218:221], v[64:67]
	v_mfma_f32_16x16x32_bf16 v[116:119], v[230:233], v[198:201], v[116:119]
	v_mfma_f32_16x16x32_bf16 v[112:115], v[238:241], v[198:201], v[112:115]
	v_mfma_f32_16x16x32_bf16 v[100:103], v[230:233], v[206:209], v[100:103]
	v_mfma_f32_16x16x32_bf16 v[96:99], v[238:241], v[206:209], v[96:99]
	v_mfma_f32_16x16x32_bf16 v[84:87], v[230:233], v[214:217], v[84:87]
	v_mfma_f32_16x16x32_bf16 v[80:83], v[238:241], v[214:217], v[80:83]
	v_mfma_f32_16x16x32_bf16 v[68:71], v[230:233], v[222:225], v[68:71]
	v_mfma_f32_16x16x32_bf16 v[64:67], v[238:241], v[222:225], v[64:67]
	s_setprio 0
	s_mov_b32 m0, s6
	v_lshl_add_u64 v[140:141], v[244:245], 0, s[10:11]
	s_barrier
	ds_read_b128 v[194:197], v153 offset:49152
	ds_read_b128 v[198:201], v153 offset:50176
	ds_read_b128 v[202:205], v153 offset:51200
	ds_read_b128 v[206:209], v153 offset:52224
	ds_read_b128 v[210:213], v153 offset:53248
	ds_read_b128 v[214:217], v153 offset:54272
	ds_read_b128 v[218:221], v153 offset:55296
	ds_read_b128 v[222:225], v153 offset:56320
	global_load_lds_dwordx4 v[140:141], off
	v_lshl_add_u64 v[140:141], v[246:247], 0, s[10:11]
	s_mov_b32 m0, s7
	s_nop 0
	global_load_lds_dwordx4 v[140:141], off
	s_barrier
	s_waitcnt lgkmcnt(0)
	s_setprio 1
	s_waitcnt lgkmcnt(0)
	v_mfma_f32_16x16x32_bf16 v[60:63], v[136:139], v[194:197], v[60:63]
	v_mfma_f32_16x16x32_bf16 v[56:59], v[172:175], v[194:197], v[56:59]
	v_mfma_f32_16x16x32_bf16 v[44:47], v[136:139], v[202:205], v[44:47]
	v_mfma_f32_16x16x32_bf16 v[40:43], v[172:175], v[202:205], v[40:43]
	v_mfma_f32_16x16x32_bf16 v[28:31], v[136:139], v[210:213], v[28:31]
	v_mfma_f32_16x16x32_bf16 v[24:27], v[172:175], v[210:213], v[24:27]
	v_mfma_f32_16x16x32_bf16 v[12:15], v[136:139], v[218:221], v[12:15]
	v_mfma_f32_16x16x32_bf16 v[8:11], v[172:175], v[218:221], v[8:11]
	v_mfma_f32_16x16x32_bf16 v[60:63], v[168:171], v[198:201], v[60:63]
	v_mfma_f32_16x16x32_bf16 v[56:59], v[176:179], v[198:201], v[56:59]
	v_mfma_f32_16x16x32_bf16 v[44:47], v[168:171], v[206:209], v[44:47]
	v_mfma_f32_16x16x32_bf16 v[40:43], v[176:179], v[206:209], v[40:43]
	v_mfma_f32_16x16x32_bf16 v[28:31], v[168:171], v[214:217], v[28:31]
	v_mfma_f32_16x16x32_bf16 v[24:27], v[176:179], v[214:217], v[24:27]
	v_mfma_f32_16x16x32_bf16 v[12:15], v[168:171], v[222:225], v[12:15]
	v_mfma_f32_16x16x32_bf16 v[8:11], v[176:179], v[222:225], v[8:11]
	s_setprio 0
	s_barrier
	s_add_u32 s28, s48, 0x40080
	s_addc_u32 s29, s49, 0
	s_add_i32 s48, s50, s53
	v_lshl_add_u64 v[136:137], s[28:29], 0, v[158:159]
	s_mov_b32 m0, s48
	s_nop 0
	global_load_lds_dwordx4 v[136:137], off
	v_lshl_add_u64 v[136:137], s[28:29], 0, v[162:163]
	s_add_i32 m0, s48, 0x2000
	s_nop 0
	global_load_lds_dwordx4 v[136:137], off
	s_waitcnt vmcnt(6)
	s_barrier
	s_setprio 1
	v_mfma_f32_16x16x32_bf16 v[52:55], v[226:229], v[194:197], v[52:55]
	v_mfma_f32_16x16x32_bf16 v[48:51], v[234:237], v[194:197], v[48:51]
	v_mfma_f32_16x16x32_bf16 v[36:39], v[226:229], v[202:205], v[36:39]
	v_mfma_f32_16x16x32_bf16 v[32:35], v[234:237], v[202:205], v[32:35]
	v_mfma_f32_16x16x32_bf16 v[20:23], v[226:229], v[210:213], v[20:23]
	v_mfma_f32_16x16x32_bf16 v[16:19], v[234:237], v[210:213], v[16:19]
	v_mfma_f32_16x16x32_bf16 v[4:7], v[226:229], v[218:221], v[4:7]
	v_mfma_f32_16x16x32_bf16 v[0:3], v[234:237], v[218:221], v[0:3]
	v_mfma_f32_16x16x32_bf16 v[52:55], v[230:233], v[198:201], v[52:55]
	v_mfma_f32_16x16x32_bf16 v[48:51], v[238:241], v[198:201], v[48:51]
	v_mfma_f32_16x16x32_bf16 v[36:39], v[230:233], v[206:209], v[36:39]
	v_mfma_f32_16x16x32_bf16 v[32:35], v[238:241], v[206:209], v[32:35]
	v_mfma_f32_16x16x32_bf16 v[20:23], v[230:233], v[214:217], v[20:23]
	v_mfma_f32_16x16x32_bf16 v[16:19], v[238:241], v[214:217], v[16:19]
	v_mfma_f32_16x16x32_bf16 v[4:7], v[230:233], v[222:225], v[4:7]
	v_mfma_f32_16x16x32_bf16 v[0:3], v[238:241], v[222:225], v[0:3]
	s_setprio 0
	s_add_i32 s74, s74, 2
	s_add_u32 s46, s46, 0x100
	s_addc_u32 s47, s47, 0
	s_add_u32 s72, s72, 0x100
	s_addc_u32 s73, s73, 0
	s_cmp_gt_u32 s74, 13
	s_barrier
	s_cbranch_scc0 .LBB0_898
	v_lshl_add_u32 v140, s44, 8, v142
	v_lshl_or_b32 v138, s26, 7, v145
	v_ashrrev_i32_e32 v141, 31, v140
	v_ashrrev_i32_e32 v139, 31, v138
	v_lshlrev_b64 v[136:137], 10, v[140:141]
	v_lshl_add_u64 v[136:137], v[136:137], 0, v[138:139]
	v_lshlrev_b64 v[136:137], 1, v[136:137]
	v_lshl_add_u64 v[168:169], s[38:39], 0, v[136:137]
	v_lshl_add_u64 v[172:173], s[40:41], 0, v[136:137]
	global_load_dwordx4 v[168:171], v[168:169], off
	v_mul_f32_e32 v124, 0xbfb8aa3b, v124
	global_load_dwordx4 v[172:175], v[172:173], off
	s_add_u32 s78, s38, 0x8000
	s_addc_u32 s79, s39, 0
	global_load_dwordx4 v[198:201], v136, s[78:79]
	s_add_u32 s80, s40, 0x8000
	s_addc_u32 s81, s41, 0
	global_load_dwordx4 v[202:205], v136, s[80:81]
	s_add_u32 s78, s38, 0x10000
	s_addc_u32 s79, s39, 0
	global_load_dwordx4 v[206:209], v136, s[78:79]
	s_add_u32 s80, s40, 0x10000
	s_addc_u32 s81, s41, 0
	global_load_dwordx4 v[210:213], v136, s[80:81]
	s_add_u32 s78, s38, 0x18000
	s_addc_u32 s79, s39, 0
	global_load_dwordx4 v[214:217], v136, s[78:79]
	s_add_u32 s80, s40, 0x18000
	s_addc_u32 s81, s41, 0
	global_load_dwordx4 v[218:221], v136, s[80:81]
	s_add_u32 s78, s38, 0x40000
	s_addc_u32 s79, s39, 0
	global_load_dwordx4 v[222:225], v136, s[78:79]
	s_add_u32 s80, s40, 0x40000
	s_addc_u32 s81, s41, 0
	global_load_dwordx4 v[226:229], v136, s[80:81]
	s_add_u32 s78, s38, 0x48000
	s_addc_u32 s79, s39, 0
	global_load_dwordx4 v[230:233], v136, s[78:79]
	s_add_u32 s80, s40, 0x48000
	s_addc_u32 s81, s41, 0
	global_load_dwordx4 v[234:237], v136, s[80:81]
	s_add_u32 s78, s38, 0x50000
	s_addc_u32 s79, s39, 0
	global_load_dwordx4 v[238:241], v136, s[78:79]
	s_add_u32 s80, s40, 0x50000
	s_addc_u32 s81, s41, 0
	global_load_dwordx4 v[242:245], v136, s[80:81]
	s_add_u32 s78, s38, 0x58000
	s_addc_u32 s79, s39, 0
	global_load_dwordx4 v[246:249], v136, s[78:79]
	s_add_u32 s80, s40, 0x58000
	s_addc_u32 s81, s41, 0
	global_load_dwordx4 v[250:253], v136, s[80:81]
	v_mul_f32_e32 v116, 0xbfb8aa3b, v116
	v_mul_f32_e32 v112, 0xbfb8aa3b, v112
	v_mul_f32_e32 v125, 0xbfb8aa3b, v125
	v_mul_f32_e32 v117, 0xbfb8aa3b, v117
	v_mul_f32_e32 v113, 0xbfb8aa3b, v113
	v_mul_f32_e32 v120, 0xbfb8aa3b, v120
	v_mul_f32_e32 v121, 0xbfb8aa3b, v121
	v_mul_f32_e32 v118, 0xbfb8aa3b, v118
	v_mul_f32_e32 v114, 0xbfb8aa3b, v114
	v_mul_f32_e32 v119, 0xbfb8aa3b, v119
	v_exp_f32_e32 v124, v124
	v_exp_f32_e32 v116, v116
	v_exp_f32_e32 v112, v112
	v_exp_f32_e32 v125, v125
	v_exp_f32_e32 v117, v117
	v_exp_f32_e32 v113, v113
	v_exp_f32_e32 v120, v120
	v_exp_f32_e32 v121, v121
	v_exp_f32_e32 v118, v118
	v_exp_f32_e32 v114, v114
	v_exp_f32_e32 v119, v119
	v_mul_f32_e32 v126, 0xbfb8aa3b, v126
	v_mul_f32_e32 v122, 0xbfb8aa3b, v122
	v_mul_f32_e32 v123, 0xbfb8aa3b, v123
	v_mul_f32_e32 v115, 0xbfb8aa3b, v115
	v_exp_f32_e32 v126, v126
	v_exp_f32_e32 v122, v122
	v_exp_f32_e32 v141, v123
	v_exp_f32_e32 v164, v115
	v_add_f32_e32 v115, 1.0, v124
	v_add_f32_e32 v116, 1.0, v116
	v_add_f32_e32 v123, 1.0, v112
	v_add_f32_e32 v124, 1.0, v125
	v_add_f32_e32 v117, 1.0, v117
	v_add_f32_e32 v125, 1.0, v113
	v_mul_f32_e32 v127, 0xbfb8aa3b, v127
	v_add_f32_e32 v120, 1.0, v120
	v_add_f32_e32 v121, 1.0, v121
	v_add_f32_e32 v166, 1.0, v118
	v_add_f32_e32 v177, 1.0, v114
	v_add_f32_e32 v178, 1.0, v119
	v_rcp_f32_e32 v112, v115
	v_rcp_f32_e32 v114, v116
	v_rcp_f32_e32 v118, v123
	v_rcp_f32_e32 v115, v117
	v_rcp_f32_e32 v119, v125
	v_exp_f32_e32 v127, v127
	v_rcp_f32_e32 v116, v120
	v_rcp_f32_e32 v113, v124
	v_rcp_f32_e32 v117, v121
	v_add_f32_e32 v126, 1.0, v126
	v_add_f32_e32 v176, 1.0, v122
	v_rcp_f32_e32 v123, v178
	v_rcp_f32_e32 v120, v126
	v_rcp_f32_e32 v124, v176
	v_rcp_f32_e32 v126, v177
	v_add_f32_e32 v127, 1.0, v127
	v_rcp_f32_e32 v122, v166
	v_rcp_f32_e32 v121, v127
	v_mul_f32_e32 v108, 0xbfb8aa3b, v108
	v_mul_f32_e32 v100, 0xbfb8aa3b, v100
	v_mul_f32_e32 v96, 0xbfb8aa3b, v96
	v_mul_f32_e32 v109, 0xbfb8aa3b, v109
	v_mul_f32_e32 v101, 0xbfb8aa3b, v101
	v_mul_f32_e32 v97, 0xbfb8aa3b, v97
	v_mul_f32_e32 v104, 0xbfb8aa3b, v104
	v_mul_f32_e32 v105, 0xbfb8aa3b, v105
	v_exp_f32_e32 v108, v108
	v_exp_f32_e32 v100, v100
	v_exp_f32_e32 v96, v96
	v_exp_f32_e32 v109, v109
	v_exp_f32_e32 v101, v101
	v_exp_f32_e32 v97, v97
	v_exp_f32_e32 v104, v104
	v_exp_f32_e32 v105, v105
	v_mul_f32_e32 v110, 0xbfb8aa3b, v110
	v_mul_f32_e32 v102, 0xbfb8aa3b, v102
	s_waitcnt vmcnt(0)
	v_lshlrev_b32_e32 v176, 16, v168
	v_and_b32_e32 v177, 0xffff0000, v168
	v_lshlrev_b32_e32 v178, 16, v172
	v_and_b32_e32 v179, 0xffff0000, v172
	v_lshlrev_b32_e32 v196, 16, v174
	v_and_b32_e32 v197, 0xffff0000, v174
	v_lshlrev_b32_e32 v194, 16, v170
	v_and_b32_e32 v195, 0xffff0000, v170
	v_pk_mul_f32 v[114:115], v[114:115], v[178:179]
	v_pk_mul_f32 v[118:119], v[118:119], v[196:197]
	v_pk_fma_f32 v[112:113], v[112:113], v[176:177], v[114:115]
	v_pk_fma_f32 v[114:115], v[116:117], v[194:195], v[118:119]
	v_add_f32_e32 v118, 1.0, v141
	v_rcp_f32_e32 v125, v118
	v_add_f32_e32 v118, 1.0, v164
	v_rcp_f32_e32 v127, v118
	v_lshlrev_b32_e32 v172, 16, v173
	v_and_b32_e32 v173, 0xffff0000, v173
	v_lshlrev_b32_e32 v168, 16, v169
	v_and_b32_e32 v169, 0xffff0000, v169
	v_pk_mul_f32 v[122:123], v[122:123], v[172:173]
	v_lshlrev_b32_e32 v118, 16, v171
	v_pk_fma_f32 v[116:117], v[120:121], v[168:169], v[122:123]
	v_lshlrev_b32_e32 v120, 16, v175
	v_and_b32_e32 v121, 0xffff0000, v175
	v_and_b32_e32 v119, 0xffff0000, v171
	v_pk_mul_f32 v[120:121], v[126:127], v[120:121]
	v_cvt_pk_bf16_f32 v112, v112, v113
	v_pk_fma_f32 v[118:119], v[124:125], v[118:119], v[120:121]
	v_cvt_pk_bf16_f32 v113, v116, v117
	v_cvt_pk_bf16_f32 v114, v114, v115
	v_cvt_pk_bf16_f32 v115, v118, v119
	v_lshl_add_u64 v[116:117], s[58:59], 0, v[136:137]
	global_store_dwordx4 v[116:117], v[112:115], off
	v_exp_f32_e32 v110, v110
	v_exp_f32_e32 v102, v102
	v_or_b32_e32 v112, 16, v140
	v_ashrrev_i32_e32 v113, 31, v112
	v_lshlrev_b64 v[112:113], 10, v[112:113]
	v_lshl_add_u64 v[112:113], v[112:113], 0, v[138:139]
	v_lshlrev_b64 v[120:121], 1, v[112:113]
	s_nop 0
	s_nop 0
	s_nop 0
	v_mul_f32_e32 v106, 0xbfb8aa3b, v106
	s_nop 0
	v_add_f32_e32 v108, 1.0, v108
	v_add_f32_e32 v100, 1.0, v100
	v_add_f32_e32 v122, 1.0, v96
	v_add_f32_e32 v109, 1.0, v109
	v_add_f32_e32 v101, 1.0, v101
	v_add_f32_e32 v123, 1.0, v97
	v_mul_f32_e32 v98, 0xbfb8aa3b, v98
	v_exp_f32_e32 v106, v106
	v_add_f32_e32 v104, 1.0, v104
	v_add_f32_e32 v105, 1.0, v105
	v_rcp_f32_e32 v96, v108
	v_rcp_f32_e32 v100, v100
	v_rcp_f32_e32 v108, v122
	v_rcp_f32_e32 v97, v109
	v_rcp_f32_e32 v101, v101
	v_rcp_f32_e32 v109, v123
	v_exp_f32_e32 v98, v98
	v_rcp_f32_e32 v104, v104
	v_rcp_f32_e32 v105, v105
	v_add_f32_e32 v110, 1.0, v110
	v_add_f32_e32 v124, 1.0, v102
	v_rcp_f32_e32 v102, v110
	v_rcp_f32_e32 v110, v124
	v_mul_f32_e32 v111, 0xbfb8aa3b, v111
	v_add_f32_e32 v106, 1.0, v106
	v_mul_f32_e32 v103, 0xbfb8aa3b, v103
	v_add_f32_e32 v141, 1.0, v98
	v_rcp_f32_e32 v98, v106
	v_exp_f32_e32 v106, v103
	v_mul_f32_e32 v99, 0xbfb8aa3b, v99
	v_mul_f32_e32 v84, 0xbfb8aa3b, v84
	v_mul_f32_e32 v85, 0xbfb8aa3b, v85
	v_mul_f32_e32 v92, 0xbfb8aa3b, v92
	v_mul_f32_e32 v80, 0xbfb8aa3b, v80
	v_mul_f32_e32 v93, 0xbfb8aa3b, v93
	v_mul_f32_e32 v81, 0xbfb8aa3b, v81
	v_exp_f32_e32 v84, v84
	v_exp_f32_e32 v85, v85
	v_exp_f32_e32 v92, v92
	v_exp_f32_e32 v80, v80
	v_exp_f32_e32 v93, v93
	v_exp_f32_e32 v81, v81
	v_mul_f32_e32 v88, 0xbfb8aa3b, v88
	v_mul_f32_e32 v89, 0xbfb8aa3b, v89
	v_exp_f32_e32 v88, v88
	v_exp_f32_e32 v89, v89
	v_add_f32_e32 v84, 1.0, v84
	v_add_f32_e32 v85, 1.0, v85
	v_add_f32_e32 v92, 1.0, v92
	v_add_f32_e32 v93, 1.0, v93
	v_rcp_f32_e32 v84, v84
	v_rcp_f32_e32 v85, v85
	v_add_f32_e32 v88, 1.0, v88
	v_add_f32_e32 v89, 1.0, v89
	v_rcp_f32_e32 v88, v88
	v_rcp_f32_e32 v89, v89
	v_mul_f32_e32 v86, 0xbfb8aa3b, v86
	v_mul_f32_e32 v82, 0xbfb8aa3b, v82
	v_mul_f32_e32 v87, 0xbfb8aa3b, v87
	v_mul_f32_e32 v83, 0xbfb8aa3b, v83
	v_mul_f32_e32 v91, 0xbfb8aa3b, v91
	v_exp_f32_e32 v91, v91
	v_mul_f32_e32 v76, 0xbfb8aa3b, v76
	v_mul_f32_e32 v68, 0xbfb8aa3b, v68
	v_exp_f32_e32 v76, v76
	v_mul_f32_e32 v72, 0xbfb8aa3b, v72
	v_mul_f32_e32 v64, 0xbfb8aa3b, v64
	v_exp_f32_e32 v72, v72
	v_mul_f32_e32 v77, 0xbfb8aa3b, v77
	v_mul_f32_e32 v69, 0xbfb8aa3b, v69
	v_exp_f32_e32 v77, v77
	v_mul_f32_e32 v73, 0xbfb8aa3b, v73
	v_mul_f32_e32 v65, 0xbfb8aa3b, v65
	v_exp_f32_e32 v73, v73
	v_mul_f32_e32 v70, 0xbfb8aa3b, v70
	v_exp_f32_e32 v70, v70
	v_mul_f32_e32 v66, 0xbfb8aa3b, v66
	s_nop 0
	v_lshlrev_b32_e32 v122, 16, v198
	v_and_b32_e32 v123, 0xffff0000, v198
	v_lshlrev_b32_e32 v124, 16, v202
	v_and_b32_e32 v125, 0xffff0000, v202
	v_lshlrev_b32_e32 v168, 16, v204
	v_and_b32_e32 v169, 0xffff0000, v204
	v_lshlrev_b32_e32 v126, 16, v200
	v_and_b32_e32 v127, 0xffff0000, v200
	v_pk_mul_f32 v[100:101], v[100:101], v[124:125]
	v_pk_mul_f32 v[108:109], v[108:109], v[168:169]
	v_pk_fma_f32 v[96:97], v[96:97], v[122:123], v[100:101]
	v_pk_fma_f32 v[100:101], v[104:105], v[126:127], v[108:109]
	v_exp_f32_e32 v105, v111
	v_rcp_f32_e32 v104, v141
	v_lshlrev_b32_e32 v108, 16, v199
	v_and_b32_e32 v109, 0xffff0000, v199
	v_add_f32_e32 v103, 1.0, v105
	v_add_f32_e32 v105, 1.0, v106
	v_rcp_f32_e32 v111, v105
	v_mul_f32_e32 v105, 0xbfb8aa3b, v107
	v_exp_f32_e32 v105, v105
	v_exp_f32_e32 v106, v99
	v_rcp_f32_e32 v103, v103
	v_lshlrev_b32_e32 v112, 16, v203
	v_add_f32_e32 v99, 1.0, v105
	v_add_f32_e32 v105, 1.0, v106
	v_rcp_f32_e32 v105, v105
	v_and_b32_e32 v113, 0xffff0000, v203
	v_rcp_f32_e32 v99, v99
	v_pk_mul_f32 v[110:111], v[110:111], v[112:113]
	v_lshlrev_b32_e32 v106, 16, v201
	v_pk_fma_f32 v[102:103], v[102:103], v[108:109], v[110:111]
	v_lshlrev_b32_e32 v108, 16, v205
	v_and_b32_e32 v109, 0xffff0000, v205
	v_and_b32_e32 v107, 0xffff0000, v201
	v_pk_mul_f32 v[104:105], v[104:105], v[108:109]
	v_cvt_pk_bf16_f32 v96, v96, v97
	v_pk_fma_f32 v[104:105], v[98:99], v[106:107], v[104:105]
	v_cvt_pk_bf16_f32 v97, v102, v103
	v_cvt_pk_bf16_f32 v98, v100, v101
	v_cvt_pk_bf16_f32 v99, v104, v105
	v_lshl_add_u64 v[100:101], s[58:59], 0, v[120:121]
	global_store_dwordx4 v[100:101], v[96:99], off
	v_add_f32_e32 v106, 1.0, v80
	v_add_f32_e32 v107, 1.0, v81
	v_or_b32_e32 v96, 32, v140
	v_ashrrev_i32_e32 v97, 31, v96
	v_lshlrev_b64 v[96:97], 10, v[96:97]
	v_lshl_add_u64 v[96:97], v[96:97], 0, v[138:139]
	v_lshlrev_b64 v[104:105], 1, v[96:97]
	s_nop 0
	s_nop 0
	s_nop 0
	v_rcp_f32_e32 v80, v92
	s_nop 0
	v_rcp_f32_e32 v92, v106
	v_rcp_f32_e32 v81, v93
	v_rcp_f32_e32 v93, v107
	v_mul_f32_e32 v71, 0xbfb8aa3b, v71
	v_exp_f32_e32 v71, v71
	v_mul_f32_e32 v78, 0xbfb8aa3b, v78
	v_exp_f32_e32 v78, v78
	v_mul_f32_e32 v75, 0xbfb8aa3b, v75
	v_add_f32_e32 v71, 1.0, v71
	v_rcp_f32_e32 v71, v71
	v_exp_f32_e32 v75, v75
	v_mul_f32_e32 v67, 0xbfb8aa3b, v67
	v_mul_f32_e32 v60, 0xbfb8aa3b, v60
	v_mul_f32_e32 v52, 0xbfb8aa3b, v52
	v_exp_f32_e32 v60, v60
	v_mul_f32_e32 v56, 0xbfb8aa3b, v56
	v_mul_f32_e32 v48, 0xbfb8aa3b, v48
	v_exp_f32_e32 v56, v56
	v_mul_f32_e32 v61, 0xbfb8aa3b, v61
	v_mul_f32_e32 v53, 0xbfb8aa3b, v53
	v_exp_f32_e32 v61, v61
	v_mul_f32_e32 v57, 0xbfb8aa3b, v57
	v_mul_f32_e32 v49, 0xbfb8aa3b, v49
	v_exp_f32_e32 v57, v57
	v_mul_f32_e32 v54, 0xbfb8aa3b, v54
	v_exp_f32_e32 v54, v54
	v_mul_f32_e32 v50, 0xbfb8aa3b, v50
	v_mul_f32_e32 v55, 0xbfb8aa3b, v55
	v_exp_f32_e32 v55, v55
	v_mul_f32_e32 v62, 0xbfb8aa3b, v62
	v_exp_f32_e32 v62, v62
	v_mul_f32_e32 v59, 0xbfb8aa3b, v59
	v_add_f32_e32 v55, 1.0, v55
	v_rcp_f32_e32 v55, v55
	v_exp_f32_e32 v59, v59
	v_mul_f32_e32 v51, 0xbfb8aa3b, v51
	v_mul_f32_e32 v44, 0xbfb8aa3b, v44
	v_mul_f32_e32 v36, 0xbfb8aa3b, v36
	v_exp_f32_e32 v44, v44
	v_mul_f32_e32 v40, 0xbfb8aa3b, v40
	v_mul_f32_e32 v32, 0xbfb8aa3b, v32
	v_exp_f32_e32 v40, v40
	v_mul_f32_e32 v45, 0xbfb8aa3b, v45
	v_mul_f32_e32 v37, 0xbfb8aa3b, v37
	v_exp_f32_e32 v45, v45
	v_mul_f32_e32 v41, 0xbfb8aa3b, v41
	v_mul_f32_e32 v33, 0xbfb8aa3b, v33
	v_exp_f32_e32 v41, v41
	v_mul_f32_e32 v38, 0xbfb8aa3b, v38
	v_exp_f32_e32 v38, v38
	v_mul_f32_e32 v34, 0xbfb8aa3b, v34
	v_mul_f32_e32 v39, 0xbfb8aa3b, v39
	v_exp_f32_e32 v39, v39
	v_mul_f32_e32 v46, 0xbfb8aa3b, v46
	v_exp_f32_e32 v46, v46
	v_mul_f32_e32 v43, 0xbfb8aa3b, v43
	v_add_f32_e32 v39, 1.0, v39
	v_rcp_f32_e32 v39, v39
	v_exp_f32_e32 v43, v43
	v_mul_f32_e32 v35, 0xbfb8aa3b, v35
	v_mul_f32_e32 v28, 0xbfb8aa3b, v28
	v_mul_f32_e32 v20, 0xbfb8aa3b, v20
	v_exp_f32_e32 v28, v28
	v_mul_f32_e32 v24, 0xbfb8aa3b, v24
	v_mul_f32_e32 v16, 0xbfb8aa3b, v16
	v_exp_f32_e32 v24, v24
	v_mul_f32_e32 v29, 0xbfb8aa3b, v29
	v_mul_f32_e32 v21, 0xbfb8aa3b, v21
	v_exp_f32_e32 v29, v29
	v_mul_f32_e32 v25, 0xbfb8aa3b, v25
	v_mul_f32_e32 v17, 0xbfb8aa3b, v17
	v_exp_f32_e32 v25, v25
	v_mul_f32_e32 v22, 0xbfb8aa3b, v22
	v_exp_f32_e32 v22, v22
	v_mul_f32_e32 v18, 0xbfb8aa3b, v18
	v_mul_f32_e32 v23, 0xbfb8aa3b, v23
	v_exp_f32_e32 v23, v23
	s_nop 0
	v_lshlrev_b32_e32 v106, 16, v206
	v_and_b32_e32 v107, 0xffff0000, v206
	v_lshlrev_b32_e32 v108, 16, v210
	v_and_b32_e32 v109, 0xffff0000, v210
	v_lshlrev_b32_e32 v112, 16, v212
	v_and_b32_e32 v113, 0xffff0000, v212
	v_pk_mul_f32 v[84:85], v[84:85], v[108:109]
	v_lshlrev_b32_e32 v110, 16, v208
	v_pk_fma_f32 v[80:81], v[80:81], v[106:107], v[84:85]
	v_pk_mul_f32 v[84:85], v[92:93], v[112:113]
	v_exp_f32_e32 v93, v86
	v_and_b32_e32 v111, 0xffff0000, v208
	v_pk_fma_f32 v[84:85], v[88:89], v[110:111], v[84:85]
	v_mul_f32_e32 v89, 0xbfb8aa3b, v90
	v_mul_f32_e32 v92, 0xbfb8aa3b, v94
	v_exp_f32_e32 v89, v89
	v_exp_f32_e32 v90, v82
	v_exp_f32_e32 v92, v92
	v_add_f32_e32 v88, 1.0, v93
	v_exp_f32_e32 v93, v87
	v_add_f32_e32 v82, 1.0, v89
	v_add_f32_e32 v89, 1.0, v90
	v_mul_f32_e32 v90, 0xbfb8aa3b, v95
	v_add_f32_e32 v86, 1.0, v92
	v_exp_f32_e32 v92, v90
	v_rcp_f32_e32 v90, v89
	v_add_f32_e32 v89, 1.0, v93
	v_rcp_f32_e32 v88, v88
	v_rcp_f32_e32 v89, v89
	v_add_f32_e32 v87, 1.0, v92
	v_lshlrev_b32_e32 v94, 16, v211
	v_and_b32_e32 v95, 0xffff0000, v211
	v_rcp_f32_e32 v86, v86
	v_rcp_f32_e32 v87, v87
	v_pk_mul_f32 v[88:89], v[88:89], v[94:95]
	v_exp_f32_e32 v94, v83
	v_lshlrev_b32_e32 v92, 16, v207
	v_and_b32_e32 v93, 0xffff0000, v207
	v_pk_fma_f32 v[86:87], v[86:87], v[92:93], v[88:89]
	v_add_f32_e32 v88, 1.0, v94
	v_add_f32_e32 v83, 1.0, v91
	v_rcp_f32_e32 v91, v88
	v_rcp_f32_e32 v82, v82
	v_rcp_f32_e32 v83, v83
	v_lshlrev_b32_e32 v92, 16, v213
	v_and_b32_e32 v93, 0xffff0000, v213
	v_lshlrev_b32_e32 v88, 16, v209
	v_and_b32_e32 v89, 0xffff0000, v209
	v_pk_mul_f32 v[90:91], v[90:91], v[92:93]
	v_cvt_pk_bf16_f32 v80, v80, v81
	v_pk_fma_f32 v[88:89], v[82:83], v[88:89], v[90:91]
	v_cvt_pk_bf16_f32 v81, v86, v87
	v_cvt_pk_bf16_f32 v82, v84, v85
	v_cvt_pk_bf16_f32 v83, v88, v89
	v_lshl_add_u64 v[84:85], s[58:59], 0, v[104:105]
	global_store_dwordx4 v[84:85], v[80:83], off
	v_exp_f32_e32 v90, v68
	v_add_f32_e32 v68, 1.0, v76
	v_or_b32_e32 v80, 48, v140
	v_ashrrev_i32_e32 v81, 31, v80
	v_lshlrev_b64 v[80:81], 10, v[80:81]
	v_lshl_add_u64 v[80:81], v[80:81], 0, v[138:139]
	v_lshlrev_b64 v[88:89], 1, v[80:81]
	s_nop 0
	s_nop 0
	s_nop 0
	s_nop 0
	v_add_f32_e32 v76, 1.0, v90
	v_exp_f32_e32 v90, v64
	v_add_f32_e32 v64, 1.0, v72
	v_rcp_f32_e32 v76, v76
	v_rcp_f32_e32 v68, v68
	v_add_f32_e32 v72, 1.0, v90
	v_exp_f32_e32 v90, v69
	v_add_f32_e32 v69, 1.0, v77
	v_rcp_f32_e32 v69, v69
	v_rcp_f32_e32 v72, v72
	v_add_f32_e32 v77, 1.0, v90
	v_rcp_f32_e32 v77, v77
	v_rcp_f32_e32 v64, v64
	v_mul_f32_e32 v30, 0xbfb8aa3b, v30
	v_exp_f32_e32 v30, v30
	v_add_f32_e32 v23, 1.0, v23
	v_rcp_f32_e32 v23, v23
	v_mul_f32_e32 v27, 0xbfb8aa3b, v27
	v_exp_f32_e32 v27, v27
	v_mul_f32_e32 v19, 0xbfb8aa3b, v19
	v_mul_f32_e32 v12, 0xbfb8aa3b, v12
	v_mul_f32_e32 v4, 0xbfb8aa3b, v4
	v_exp_f32_e32 v12, v12
	v_mul_f32_e32 v8, 0xbfb8aa3b, v8
	v_mul_f32_e32 v0, 0xbfb8aa3b, v0
	v_exp_f32_e32 v8, v8
	v_mul_f32_e32 v13, 0xbfb8aa3b, v13
	v_mul_f32_e32 v5, 0xbfb8aa3b, v5
	v_exp_f32_e32 v13, v13
	v_mul_f32_e32 v9, 0xbfb8aa3b, v9
	v_mul_f32_e32 v1, 0xbfb8aa3b, v1
	v_exp_f32_e32 v9, v9
	v_mul_f32_e32 v6, 0xbfb8aa3b, v6
	v_exp_f32_e32 v6, v6
	v_mul_f32_e32 v2, 0xbfb8aa3b, v2
	v_mul_f32_e32 v7, 0xbfb8aa3b, v7
	v_exp_f32_e32 v7, v7
	v_mul_f32_e32 v14, 0xbfb8aa3b, v14
	v_exp_f32_e32 v14, v14
	v_mul_f32_e32 v11, 0xbfb8aa3b, v11
	v_add_f32_e32 v7, 1.0, v7
	v_rcp_f32_e32 v7, v7
	v_exp_f32_e32 v11, v11
	v_mul_f32_e32 v3, 0xbfb8aa3b, v3
	s_and_b64 vcc, exec, s[8:9]
	s_mov_b32 s26, s22
	s_mov_b32 s44, s20
	s_mov_b64 s[48:49], s[42:43]
	s_mov_b64 s[46:47], s[24:25]
	s_nop 0
	v_lshlrev_b32_e32 v90, 16, v214
	v_and_b32_e32 v91, 0xffff0000, v214
	v_exp_f32_e32 v80, v65
	v_add_f32_e32 v65, 1.0, v73
	v_lshlrev_b32_e32 v92, 16, v218
	v_and_b32_e32 v93, 0xffff0000, v218
	v_add_f32_e32 v73, 1.0, v80
	v_rcp_f32_e32 v73, v73
	v_rcp_f32_e32 v65, v65
	v_pk_mul_f32 v[76:77], v[76:77], v[92:93]
	s_nop 0
	v_pk_fma_f32 v[68:69], v[68:69], v[90:91], v[76:77]
	v_lshlrev_b32_e32 v90, 16, v220
	v_and_b32_e32 v91, 0xffff0000, v220
	v_lshlrev_b32_e32 v76, 16, v216
	v_and_b32_e32 v77, 0xffff0000, v216
	v_pk_mul_f32 v[72:73], v[72:73], v[90:91]
	s_nop 0
	v_pk_fma_f32 v[72:73], v[64:65], v[76:77], v[72:73]
	v_add_f32_e32 v65, 1.0, v70
	v_mul_f32_e32 v70, 0xbfb8aa3b, v74
	v_exp_f32_e32 v74, v70
	v_exp_f32_e32 v76, v66
	v_rcp_f32_e32 v70, v65
	v_add_f32_e32 v64, 1.0, v78
	v_add_f32_e32 v65, 1.0, v74
	v_mul_f32_e32 v74, 0xbfb8aa3b, v79
	v_rcp_f32_e32 v66, v65
	v_add_f32_e32 v65, 1.0, v76
	v_exp_f32_e32 v76, v74
	v_rcp_f32_e32 v74, v65
	v_rcp_f32_e32 v64, v64
	v_lshlrev_b32_e32 v78, 16, v219
	v_add_f32_e32 v65, 1.0, v76
	v_rcp_f32_e32 v65, v65
	v_and_b32_e32 v79, 0xffff0000, v219
	v_pk_mul_f32 v[70:71], v[70:71], v[78:79]
	v_exp_f32_e32 v78, v67
	v_lshlrev_b32_e32 v76, 16, v215
	v_and_b32_e32 v77, 0xffff0000, v215
	v_pk_fma_f32 v[70:71], v[64:65], v[76:77], v[70:71]
	v_add_f32_e32 v64, 1.0, v75
	v_rcp_f32_e32 v67, v64
	v_add_f32_e32 v64, 1.0, v78
	v_rcp_f32_e32 v75, v64
	v_lshlrev_b32_e32 v76, 16, v221
	v_and_b32_e32 v77, 0xffff0000, v221
	v_lshlrev_b32_e32 v64, 16, v217
	v_and_b32_e32 v65, 0xffff0000, v217
	v_pk_mul_f32 v[74:75], v[74:75], v[76:77]
	s_nop 0
	v_pk_fma_f32 v[74:75], v[66:67], v[64:65], v[74:75]
	v_cvt_pk_bf16_f32 v64, v68, v69
	v_cvt_pk_bf16_f32 v65, v70, v71
	v_cvt_pk_bf16_f32 v66, v72, v73
	v_cvt_pk_bf16_f32 v67, v74, v75
	v_lshl_add_u64 v[68:69], s[58:59], 0, v[88:89]
	v_lshl_add_u64 v[72:73], v[136:137], 0, s[0:1]
	global_store_dwordx4 v[68:69], v[64:67], off
	s_nop 0
	s_nop 0
	s_nop 0
	s_nop 0
	v_exp_f32_e32 v74, v52
	v_add_f32_e32 v52, 1.0, v60
	v_rcp_f32_e32 v52, v52
	v_add_f32_e32 v60, 1.0, v74
	v_exp_f32_e32 v74, v48
	v_add_f32_e32 v48, 1.0, v56
	v_rcp_f32_e32 v60, v60
	v_rcp_f32_e32 v48, v48
	v_add_f32_e32 v56, 1.0, v74
	v_exp_f32_e32 v74, v53
	v_add_f32_e32 v53, 1.0, v61
	v_rcp_f32_e32 v53, v53
	v_rcp_f32_e32 v56, v56
	v_add_f32_e32 v61, 1.0, v74
	v_rcp_f32_e32 v61, v61
	s_nop 0
	v_lshlrev_b32_e32 v76, 16, v226
	v_and_b32_e32 v77, 0xffff0000, v226
	v_lshlrev_b32_e32 v74, 16, v222
	v_and_b32_e32 v75, 0xffff0000, v222
	v_exp_f32_e32 v64, v49
	v_add_f32_e32 v49, 1.0, v57
	v_rcp_f32_e32 v49, v49
	v_pk_mul_f32 v[60:61], v[60:61], v[76:77]
	v_add_f32_e32 v57, 1.0, v64
	v_rcp_f32_e32 v57, v57
	v_pk_fma_f32 v[52:53], v[52:53], v[74:75], v[60:61]
	v_lshlrev_b32_e32 v74, 16, v228
	v_and_b32_e32 v75, 0xffff0000, v228
	v_lshlrev_b32_e32 v60, 16, v224
	v_and_b32_e32 v61, 0xffff0000, v224
	v_pk_mul_f32 v[56:57], v[56:57], v[74:75]
	s_nop 0
	v_pk_fma_f32 v[56:57], v[48:49], v[60:61], v[56:57]
	v_add_f32_e32 v49, 1.0, v54
	v_mul_f32_e32 v54, 0xbfb8aa3b, v58
	v_exp_f32_e32 v58, v54
	v_exp_f32_e32 v60, v50
	v_rcp_f32_e32 v54, v49
	v_add_f32_e32 v48, 1.0, v62
	v_add_f32_e32 v49, 1.0, v58
	v_mul_f32_e32 v58, 0xbfb8aa3b, v63
	v_rcp_f32_e32 v50, v49
	v_add_f32_e32 v49, 1.0, v60
	v_exp_f32_e32 v60, v58
	v_rcp_f32_e32 v58, v49
	v_rcp_f32_e32 v48, v48
	v_lshlrev_b32_e32 v62, 16, v227
	v_add_f32_e32 v49, 1.0, v60
	v_rcp_f32_e32 v49, v49
	v_and_b32_e32 v63, 0xffff0000, v227
	v_pk_mul_f32 v[54:55], v[54:55], v[62:63]
	v_exp_f32_e32 v62, v51
	v_lshlrev_b32_e32 v60, 16, v223
	v_and_b32_e32 v61, 0xffff0000, v223
	v_pk_fma_f32 v[54:55], v[48:49], v[60:61], v[54:55]
	v_add_f32_e32 v48, 1.0, v59
	v_rcp_f32_e32 v51, v48
	v_add_f32_e32 v48, 1.0, v62
	v_rcp_f32_e32 v59, v48
	v_lshlrev_b32_e32 v60, 16, v229
	v_and_b32_e32 v61, 0xffff0000, v229
	v_lshlrev_b32_e32 v48, 16, v225
	v_and_b32_e32 v49, 0xffff0000, v225
	v_pk_mul_f32 v[58:59], v[58:59], v[60:61]
	s_nop 0
	v_pk_fma_f32 v[58:59], v[50:51], v[48:49], v[58:59]
	v_cvt_pk_bf16_f32 v48, v52, v53
	v_cvt_pk_bf16_f32 v49, v54, v55
	v_cvt_pk_bf16_f32 v50, v56, v57
	v_cvt_pk_bf16_f32 v51, v58, v59
	v_lshl_add_u64 v[52:53], s[58:59], 0, v[72:73]
	v_lshl_add_u64 v[56:57], v[136:137], 0, s[12:13]
	global_store_dwordx4 v[52:53], v[48:51], off
	s_nop 0
	s_nop 0
	s_nop 0
	s_nop 0
	v_exp_f32_e32 v58, v36
	v_add_f32_e32 v36, 1.0, v44
	v_rcp_f32_e32 v36, v36
	v_add_f32_e32 v44, 1.0, v58
	v_exp_f32_e32 v58, v32
	v_add_f32_e32 v32, 1.0, v40
	v_rcp_f32_e32 v44, v44
	v_rcp_f32_e32 v32, v32
	v_add_f32_e32 v40, 1.0, v58
	v_exp_f32_e32 v58, v37
	v_add_f32_e32 v37, 1.0, v45
	v_rcp_f32_e32 v37, v37
	v_rcp_f32_e32 v40, v40
	v_add_f32_e32 v45, 1.0, v58
	v_rcp_f32_e32 v45, v45
	s_nop 0
	v_lshlrev_b32_e32 v60, 16, v234
	v_and_b32_e32 v61, 0xffff0000, v234
	v_lshlrev_b32_e32 v58, 16, v230
	v_and_b32_e32 v59, 0xffff0000, v230
	v_exp_f32_e32 v48, v33
	v_add_f32_e32 v33, 1.0, v41
	v_rcp_f32_e32 v33, v33
	v_pk_mul_f32 v[44:45], v[44:45], v[60:61]
	v_add_f32_e32 v41, 1.0, v48
	v_rcp_f32_e32 v41, v41
	v_pk_fma_f32 v[36:37], v[36:37], v[58:59], v[44:45]
	v_lshlrev_b32_e32 v58, 16, v236
	v_and_b32_e32 v59, 0xffff0000, v236
	v_lshlrev_b32_e32 v44, 16, v232
	v_and_b32_e32 v45, 0xffff0000, v232
	v_pk_mul_f32 v[40:41], v[40:41], v[58:59]
	s_nop 0
	v_pk_fma_f32 v[40:41], v[32:33], v[44:45], v[40:41]
	v_add_f32_e32 v33, 1.0, v38
	v_mul_f32_e32 v38, 0xbfb8aa3b, v42
	v_exp_f32_e32 v42, v38
	v_exp_f32_e32 v44, v34
	v_rcp_f32_e32 v38, v33
	v_add_f32_e32 v32, 1.0, v46
	v_add_f32_e32 v33, 1.0, v42
	v_mul_f32_e32 v42, 0xbfb8aa3b, v47
	v_rcp_f32_e32 v34, v33
	v_add_f32_e32 v33, 1.0, v44
	v_exp_f32_e32 v44, v42
	v_rcp_f32_e32 v42, v33
	v_rcp_f32_e32 v32, v32
	v_lshlrev_b32_e32 v46, 16, v235
	v_add_f32_e32 v33, 1.0, v44
	v_rcp_f32_e32 v33, v33
	v_and_b32_e32 v47, 0xffff0000, v235
	v_pk_mul_f32 v[38:39], v[38:39], v[46:47]
	v_exp_f32_e32 v46, v35
	v_lshlrev_b32_e32 v44, 16, v231
	v_and_b32_e32 v45, 0xffff0000, v231
	v_pk_fma_f32 v[38:39], v[32:33], v[44:45], v[38:39]
	v_add_f32_e32 v32, 1.0, v43
	v_rcp_f32_e32 v35, v32
	v_add_f32_e32 v32, 1.0, v46
	v_rcp_f32_e32 v43, v32
	v_lshlrev_b32_e32 v44, 16, v237
	v_and_b32_e32 v45, 0xffff0000, v237
	v_lshlrev_b32_e32 v32, 16, v233
	v_and_b32_e32 v33, 0xffff0000, v233
	v_pk_mul_f32 v[42:43], v[42:43], v[44:45]
	s_nop 0
	v_pk_fma_f32 v[42:43], v[34:35], v[32:33], v[42:43]
	v_cvt_pk_bf16_f32 v32, v36, v37
	v_cvt_pk_bf16_f32 v33, v38, v39
	v_cvt_pk_bf16_f32 v34, v40, v41
	v_cvt_pk_bf16_f32 v35, v42, v43
	v_lshl_add_u64 v[36:37], s[58:59], 0, v[56:57]
	v_lshl_add_u64 v[40:41], v[136:137], 0, s[14:15]
	global_store_dwordx4 v[36:37], v[32:35], off
	s_nop 0
	s_nop 0
	s_nop 0
	s_nop 0
	v_exp_f32_e32 v42, v20
	v_add_f32_e32 v20, 1.0, v28
	v_rcp_f32_e32 v20, v20
	v_add_f32_e32 v28, 1.0, v42
	v_exp_f32_e32 v42, v16
	v_add_f32_e32 v16, 1.0, v24
	v_rcp_f32_e32 v28, v28
	v_rcp_f32_e32 v16, v16
	v_add_f32_e32 v24, 1.0, v42
	v_exp_f32_e32 v42, v21
	v_add_f32_e32 v21, 1.0, v29
	v_rcp_f32_e32 v21, v21
	v_rcp_f32_e32 v24, v24
	v_add_f32_e32 v29, 1.0, v42
	v_rcp_f32_e32 v29, v29
	s_nop 0
	v_lshlrev_b32_e32 v44, 16, v242
	v_and_b32_e32 v45, 0xffff0000, v242
	v_lshlrev_b32_e32 v42, 16, v238
	v_and_b32_e32 v43, 0xffff0000, v238
	v_exp_f32_e32 v32, v17
	v_add_f32_e32 v17, 1.0, v25
	v_rcp_f32_e32 v17, v17
	v_pk_mul_f32 v[28:29], v[28:29], v[44:45]
	v_add_f32_e32 v25, 1.0, v32
	v_rcp_f32_e32 v25, v25
	v_pk_fma_f32 v[20:21], v[20:21], v[42:43], v[28:29]
	v_lshlrev_b32_e32 v42, 16, v244
	v_and_b32_e32 v43, 0xffff0000, v244
	v_lshlrev_b32_e32 v28, 16, v240
	v_and_b32_e32 v29, 0xffff0000, v240
	v_pk_mul_f32 v[24:25], v[24:25], v[42:43]
	s_nop 0
	v_pk_fma_f32 v[24:25], v[16:17], v[28:29], v[24:25]
	v_add_f32_e32 v17, 1.0, v22
	v_mul_f32_e32 v22, 0xbfb8aa3b, v26
	v_exp_f32_e32 v26, v22
	v_exp_f32_e32 v28, v18
	v_rcp_f32_e32 v22, v17
	v_add_f32_e32 v16, 1.0, v30
	v_add_f32_e32 v17, 1.0, v26
	v_mul_f32_e32 v26, 0xbfb8aa3b, v31
	v_rcp_f32_e32 v18, v17
	v_add_f32_e32 v17, 1.0, v28
	v_exp_f32_e32 v28, v26
	v_rcp_f32_e32 v26, v17
	v_rcp_f32_e32 v16, v16
	v_lshlrev_b32_e32 v30, 16, v243
	v_add_f32_e32 v17, 1.0, v28
	v_rcp_f32_e32 v17, v17
	v_and_b32_e32 v31, 0xffff0000, v243
	v_pk_mul_f32 v[22:23], v[22:23], v[30:31]
	v_exp_f32_e32 v30, v19
	v_lshlrev_b32_e32 v28, 16, v239
	v_and_b32_e32 v29, 0xffff0000, v239
	v_pk_fma_f32 v[22:23], v[16:17], v[28:29], v[22:23]
	v_add_f32_e32 v16, 1.0, v27
	v_rcp_f32_e32 v19, v16
	v_add_f32_e32 v16, 1.0, v30
	v_rcp_f32_e32 v27, v16
	v_lshlrev_b32_e32 v28, 16, v245
	v_and_b32_e32 v29, 0xffff0000, v245
	v_lshlrev_b32_e32 v16, 16, v241
	v_and_b32_e32 v17, 0xffff0000, v241
	v_pk_mul_f32 v[26:27], v[26:27], v[28:29]
	s_nop 0
	v_pk_fma_f32 v[26:27], v[18:19], v[16:17], v[26:27]
	v_cvt_pk_bf16_f32 v16, v20, v21
	v_cvt_pk_bf16_f32 v17, v22, v23
	v_cvt_pk_bf16_f32 v18, v24, v25
	v_cvt_pk_bf16_f32 v19, v26, v27
	v_lshl_add_u64 v[20:21], s[58:59], 0, v[40:41]
	v_lshl_add_u64 v[24:25], v[136:137], 0, s[16:17]
	global_store_dwordx4 v[20:21], v[16:19], off
	s_nop 0
	s_nop 0
	s_nop 0
	s_nop 0
	v_exp_f32_e32 v26, v4
	v_add_f32_e32 v4, 1.0, v12
	v_rcp_f32_e32 v4, v4
	v_add_f32_e32 v12, 1.0, v26
	v_exp_f32_e32 v26, v0
	v_add_f32_e32 v0, 1.0, v8
	v_rcp_f32_e32 v12, v12
	v_rcp_f32_e32 v0, v0
	v_add_f32_e32 v8, 1.0, v26
	v_exp_f32_e32 v26, v5
	v_add_f32_e32 v5, 1.0, v13
	v_rcp_f32_e32 v5, v5
	v_rcp_f32_e32 v8, v8
	v_add_f32_e32 v13, 1.0, v26
	v_rcp_f32_e32 v13, v13
	s_nop 0
	v_lshlrev_b32_e32 v28, 16, v250
	v_and_b32_e32 v29, 0xffff0000, v250
	v_lshlrev_b32_e32 v26, 16, v246
	v_and_b32_e32 v27, 0xffff0000, v246
	v_exp_f32_e32 v16, v1
	v_add_f32_e32 v1, 1.0, v9
	v_rcp_f32_e32 v1, v1
	v_pk_mul_f32 v[12:13], v[12:13], v[28:29]
	v_add_f32_e32 v9, 1.0, v16
	v_rcp_f32_e32 v9, v9
	v_pk_fma_f32 v[4:5], v[4:5], v[26:27], v[12:13]
	v_lshlrev_b32_e32 v26, 16, v252
	v_and_b32_e32 v27, 0xffff0000, v252
	v_lshlrev_b32_e32 v12, 16, v248
	v_and_b32_e32 v13, 0xffff0000, v248
	v_pk_mul_f32 v[8:9], v[8:9], v[26:27]
	s_nop 0
	v_pk_fma_f32 v[8:9], v[0:1], v[12:13], v[8:9]
	v_add_f32_e32 v1, 1.0, v6
	v_mul_f32_e32 v6, 0xbfb8aa3b, v10
	v_exp_f32_e32 v10, v6
	v_exp_f32_e32 v12, v2
	v_rcp_f32_e32 v6, v1
	v_add_f32_e32 v0, 1.0, v14
	v_add_f32_e32 v1, 1.0, v10
	v_mul_f32_e32 v10, 0xbfb8aa3b, v15
	v_rcp_f32_e32 v2, v1
	v_add_f32_e32 v1, 1.0, v12
	v_exp_f32_e32 v12, v10
	v_rcp_f32_e32 v10, v1
	v_rcp_f32_e32 v0, v0
	v_lshlrev_b32_e32 v14, 16, v251
	v_add_f32_e32 v1, 1.0, v12
	v_rcp_f32_e32 v1, v1
	v_and_b32_e32 v15, 0xffff0000, v251
	v_pk_mul_f32 v[6:7], v[6:7], v[14:15]
	v_exp_f32_e32 v14, v3
	v_lshlrev_b32_e32 v12, 16, v247
	v_and_b32_e32 v13, 0xffff0000, v247
	v_pk_fma_f32 v[6:7], v[0:1], v[12:13], v[6:7]
	v_add_f32_e32 v0, 1.0, v11
	v_rcp_f32_e32 v3, v0
	v_add_f32_e32 v0, 1.0, v14
	v_rcp_f32_e32 v11, v0
	v_lshlrev_b32_e32 v12, 16, v253
	v_and_b32_e32 v13, 0xffff0000, v253
	v_lshlrev_b32_e32 v0, 16, v249
	v_and_b32_e32 v1, 0xffff0000, v249
	v_pk_mul_f32 v[10:11], v[10:11], v[12:13]
	s_nop 0
	v_pk_fma_f32 v[10:11], v[2:3], v[0:1], v[10:11]
	v_cvt_pk_bf16_f32 v0, v4, v5
	v_cvt_pk_bf16_f32 v1, v6, v7
	v_cvt_pk_bf16_f32 v2, v8, v9
	v_cvt_pk_bf16_f32 v3, v10, v11
	v_lshl_add_u64 v[4:5], s[58:59], 0, v[24:25]
	global_store_dwordx4 v[4:5], v[0:3], off
	s_cbranch_vccz .LBB0_895
	s_waitcnt vmcnt(0)
	s_cmpk_gt_u32 s3, 0xff
	s_cbranch_scc1 .LBB0_902
	s_barrier
